# baseline (speedup 1.0000x reference)
; __device__ __forceinline__ void attn_item(KP P, int l, bool isS, int b, int c, int hp, char* smem) {
;     ...
;   const int hb = tid >> 8, ht = tid & 255, wq = (tid >> 6) & 3, lane = tid & 63;
;   const int fr = lane & 15, fq = lane >> 4;
;   const int h = hp * 2 + hb;
;   char* sm = smem + hb * 45312;
;   u16* Ks = (u16*)sm;
;   u16* Vs = (u16*)(sm + 17408);
;   u16* Ps = (u16*)(sm + 34816) + wq * (16 * 72);
;   float* Bi = (float*)(sm + 34816 + 9216);
;   const int rbq = isS ? NP + b * 16 : b * 4096 + c * 64;
;   const int nq = isS ? 16 : 64;
;   for (int i = ht; i < 257; i += 256) Bi[i] = P->rel_bias[((long)l * 16 + h) * 257 + i];
;   bf16x8 qf[4];
;   {
;     int qi = wq * 16 + fr; if (qi > nq - 1) qi = nq - 1;
;     const u16* qp = PROJ + (long)(rbq + qi) * NC + OQ + h * 128 + fq * 8;
; #pragma unroll
;     for (int ks = 0; ks < 4; ++ks) qf[ks] = as_bf16x8(*(const uint4*)(qp + ks * 32));
;   }
;   f32x4 o[8] = {};
;   float mrow = -1e30f, lrow = 0.f;
;   const int t0 = isS ? 0 : (c >= 8 ? 0 : 8 - c);
;   const float scl = 0.08838834764831845f;
;   uint4 kpre[4], vpre[4];
;   float4 rk[4][2], rv[4][2];
;     ...
;   ATT_LOAD(t0);
.LBB0_516:
	s_or_b64 exec, exec, s[0:1]
	s_lshr_b64 s[0:1], s[4:5], 12
	s_lshr_b32 s1, s5, 12
	v_cndmask_b32_e64 v1, 0, 1, s[6:7]
	s_mul_i32 s1, s1, 0xba00000
	s_mul_hi_u32 s21, s0, 0xba00000
	s_mul_i32 s23, s0, 0xba00000
	v_readfirstlane_b32 s0, v1
	s_add_i32 s21, s21, s1
	s_lshl_b32 s0, s0, 11
	v_readlane_b32 s1, v251, 1
	s_add_i32 s18, s1, s0
	s_lshl_b32 s0, s14, 5
	s_and_b32 s0, s0, 32
	v_readlane_b32 s1, v251, 0
	s_ashr_i32 s19, s18, 31
	s_and_b32 s20, s4, 0xfffff000
	s_or_b32 s35, s0, s1
	s_add_u32 s8, s10, s12
	s_addc_u32 s9, s11, s13
	s_add_u32 s0, s8, 0x17a00000
	s_addc_u32 s1, s9, 0
	s_lshl_b32 s15, s14, 11
	v_and_b32_e32 v57, 15, v56
	s_lshl_b32 s38, s35, 6
	s_and_b32 s39, s15, 0x7ffff000
	v_lshrrev_b32_e32 v63, 2, v56
	s_or_b32 s15, s38, s39
	v_and_or_b32 v64, v63, 48, v57
	v_or_b32_e32 v111, s15, v64
	v_lshlrev_b32_e32 v0, 7, v0
	v_mul_lo_u32 v2, v111, s31
	v_ashrrev_i32_e32 v1, 31, v0
	v_lshl_add_u64 v[8:9], s[0:1], 0, v[2:3]
	v_lshlrev_b64 v[100:101], 1, v[0:1]
	v_lshl_add_u64 v[8:9], v[8:9], 0, v[100:101]
	v_and_b32_e32 v2, 48, v56
	v_lshl_add_u64 v[8:9], v[8:9], 0, v[2:3]
	s_mov_b64 s[42:43], 0x5800
	v_lshl_add_u64 v[20:21], v[8:9], 0, s[42:43]
	s_movk_i32 s42, 0x5000
	v_add_co_u32_e32 v16, vcc, s42, v8
	s_sub_i32 s42, 8, s35
	s_cmp_lt_u32 s35, 8
	s_cselect_b32 s35, s42, 0
	s_addk_i32 s38, 0xfe00
	s_lshl_b32 s42, s35, 6
	v_lshl_add_u64 v[24:25], s[0:1], 0, v[100:101]
	s_ashr_i32 s1, s38, 31
	s_add_u32 s0, s38, s39
	v_lshrrev_b32_sdwa v65, v232, v56 dst_sel:DWORD dst_unused:UNUSED_PAD src0_sel:DWORD src1_sel:BYTE_0
	s_addc_u32 s1, s1, 0
	v_lshlrev_b32_e32 v58, 4, v57
	v_mov_b32_e32 v59, v3
	v_or_b32_e32 v60, s42, v65
	v_mov_b32_e32 v61, v3
	v_lshl_add_u64 v[48:49], v[24:25], 0, v[58:59]
	v_lshl_add_u64 v[24:25], s[0:1], 0, v[60:61]
	v_addc_co_u32_e32 v17, vcc, 0, v9, vcc
	v_mad_u64_u32 v[26:27], s[38:39], v24, s31, v[48:49]
	s_movk_i32 s43, 0x6000
	v_mad_i32_i24 v27, v25, s31, v27
	v_add_co_u32_e32 v24, vcc, s43, v26
	s_movk_i32 s46, 0x7000
	s_nop 0
	v_addc_co_u32_e32 v25, vcc, 0, v27, vcc
	v_or_b32_e32 v32, 16, v60
	v_mov_b32_e32 v33, v3
	v_add_co_u32_e32 v28, vcc, s46, v26
	v_lshl_add_u64 v[32:33], s[0:1], 0, v[32:33]
	s_nop 0
	v_addc_co_u32_e32 v29, vcc, 0, v27, vcc
	v_mad_u64_u32 v[34:35], s[38:39], v32, s31, v[48:49]
	v_mad_i32_i24 v35, v33, s31, v35
	v_add_co_u32_e32 v32, vcc, s43, v34
	v_or_b32_e32 v40, 32, v60
	s_nop 0
	v_addc_co_u32_e32 v33, vcc, 0, v35, vcc
	v_mov_b32_e32 v41, v3
	v_add_co_u32_e32 v36, vcc, s46, v34
	v_lshl_add_u64 v[40:41], s[0:1], 0, v[40:41]
	s_nop 0
	v_addc_co_u32_e32 v37, vcc, 0, v35, vcc
	v_mad_u64_u32 v[42:43], s[38:39], v40, s31, v[48:49]
	v_mad_i32_i24 v43, v41, s31, v43
	v_add_co_u32_e32 v40, vcc, s43, v42
	v_or_b32_e32 v50, 48, v60
	s_nop 0
	v_addc_co_u32_e32 v41, vcc, 0, v43, vcc
	v_mov_b32_e32 v51, v3
	v_add_co_u32_e32 v44, vcc, s46, v42
	v_lshl_add_u64 v[50:51], s[0:1], 0, v[50:51]
	s_nop 0
	v_addc_co_u32_e32 v45, vcc, 0, v43, vcc
	v_mad_u64_u32 v[48:49], s[0:1], v50, s31, v[48:49]
	v_mad_i32_i24 v49, v51, s31, v49
	v_add_co_u32_e32 v50, vcc, s43, v48
	global_load_dwordx4 v[8:11], v[20:21], off offset:64
	global_load_dwordx4 v[12:15], v[20:21], off offset:128
	s_nop 0
	global_load_dwordx4 v[16:19], v[16:17], off offset:2048
	s_nop 0
	global_load_dwordx4 v[20:23], v[20:21], off offset:192
	v_addc_co_u32_e32 v51, vcc, 0, v49, vcc
	v_add_co_u32_e32 v52, vcc, s46, v48
	global_load_dwordx4 v[24:27], v[24:25], off offset:2048
	s_nop 0
	global_load_dwordx4 v[28:31], v[28:29], off offset:2048
	v_addc_co_u32_e32 v53, vcc, 0, v49, vcc
	global_load_dwordx4 v[32:35], v[32:33], off offset:2048
	s_nop 0
	global_load_dwordx4 v[36:39], v[36:37], off offset:2048
	s_nop 0
	global_load_dwordx4 v[40:43], v[40:41], off offset:2048
	s_nop 0
	global_load_dwordx4 v[44:47], v[44:45], off offset:2048
	s_nop 0
	global_load_dwordx4 v[48:51], v[50:51], off offset:2048
	s_nop 0
	global_load_dwordx4 v[52:55], v[52:53], off offset:2048
	v_and_b32_e32 v62, 63, v56
	v_add_u32_e32 v66, v110, v2
	v_lshlrev_b32_e32 v2, 2, v62
	v_xor_b32_e32 v113, 0x80, v2
	v_bfe_u32 v2, v56, 2, 4
	v_mul_u32_u24_e32 v68, 0x120, v2
	v_mul_u32_u24_e32 v2, 0x90, v65
	s_add_i32 s0, s35, -1
	s_add_i32 s1, s42, 0xfffffe00
	v_and_b32_e32 v112, 12, v63
	v_lshlrev_b32_e32 v56, 3, v56
	v_lshlrev_b32_e32 v2, 1, v2
	s_add_u32 s38, s12, s23
	v_and_b32_e32 v56, 24, v56
	v_add3_u32 v114, v110, v58, v2
	v_sub_u32_e32 v2, v64, v112
	s_addc_u32 s39, s13, s21
	v_add_u32_e32 v67, v110, v56
	v_mul_u32_u24_e32 v69, 0x120, v57
	v_subrev_u32_e32 v115, s42, v2
	v_add_u32_e32 v2, s18, v60
	v_mov_b64_e32 v[56:57], s[38:39]
	v_mad_i64_i32 v[56:57], s[38:39], v2, s31, v[56:57]
	s_add_u32 s18, s20, s18
	v_lshl_add_u64 v[56:57], v[56:57], 0, v[58:59]
	s_addc_u32 s19, s5, s19
	v_add_u32_e32 v2, 0x70, v60
	v_lshl_add_u64 v[102:103], s[10:11], 0, v[56:57]
	v_lshl_add_u64 v[56:57], s[18:19], 0, v[2:3]
	v_mov_b64_e32 v[62:63], s[12:13]
	v_mad_u64_u32 v[64:65], s[12:13], v56, s31, v[62:63]
	v_mov_b32_e32 v2, v65
	v_mad_u64_u32 v[56:57], s[12:13], v57, s31, v[2:3]
	v_mov_b32_e32 v65, v56
	v_lshl_add_u64 v[56:57], v[64:65], 0, v[58:59]
	v_add_u32_e32 v2, 0x60, v60
	v_lshl_add_u64 v[104:105], s[10:11], 0, v[56:57]
	v_lshl_add_u64 v[56:57], s[18:19], 0, v[2:3]
	v_mad_u64_u32 v[64:65], s[12:13], v56, s31, v[62:63]
	v_mov_b32_e32 v2, v65
	v_mad_u64_u32 v[56:57], s[12:13], v57, s31, v[2:3]
	v_mov_b32_e32 v65, v56
	v_lshl_add_u64 v[56:57], v[64:65], 0, v[58:59]
	v_add_u32_e32 v2, 0x50, v60
	v_lshl_add_u64 v[106:107], s[10:11], 0, v[56:57]
	v_lshl_add_u64 v[56:57], s[18:19], 0, v[2:3]
	v_mad_u64_u32 v[60:61], s[12:13], v56, s31, v[62:63]
	v_mov_b32_e32 v2, v61
	v_mad_u64_u32 v[56:57], s[12:13], v57, s31, v[2:3]
	v_mov_b32_e32 v61, v56
	v_lshl_add_u64 v[56:57], v[60:61], 0, v[58:59]
	v_mov_b32_e32 v117, 0
	s_mov_b32 s15, 0
	v_lshl_add_u64 v[108:109], s[10:11], 0, v[56:57]
	v_mov_b32_e32 v118, 0xf149f2ca
	v_add_u32_e32 v2, v66, v69
	v_add_u32_e32 v116, v67, v68
	v_mov_b32_e32 v68, 0
	v_mov_b32_e32 v69, v117
	v_mov_b32_e32 v70, v117
	v_mov_b32_e32 v71, v117
	v_mov_b32_e32 v76, 0
	v_mov_b32_e32 v77, v117
	v_mov_b32_e32 v78, v117
	v_mov_b32_e32 v79, v117
	v_mov_b32_e32 v72, 0
	v_mov_b32_e32 v73, v117
	v_mov_b32_e32 v74, v117
	v_mov_b32_e32 v75, v117
	v_mov_b32_e32 v60, 0
	v_mov_b32_e32 v61, v117
	v_mov_b32_e32 v62, v117
	v_mov_b32_e32 v63, v117
	v_mov_b32_e32 v56, 0
	v_mov_b32_e32 v57, v117
	v_mov_b32_e32 v58, v117
	v_mov_b32_e32 v59, v117
	v_mov_b32_e32 v64, 0
	v_mov_b32_e32 v65, v117
	v_mov_b32_e32 v66, v117
	v_mov_b32_e32 v67, v117
	v_mov_b32_e32 v80, 0
	v_mov_b32_e32 v81, v117
	v_mov_b32_e32 v82, v117
	v_mov_b32_e32 v83, v117
	v_mov_b32_e32 v84, 0
	v_mov_b32_e32 v85, v117
	v_mov_b32_e32 v86, v117
	v_mov_b32_e32 v87, v117
; __device__ __forceinline__ void attn_item(KP P, int l, bool isS, int b, int c, int hp, char* smem) {
;     ...
; #pragma unroll
;     for (int i = 0; i < 4; ++i) {
;       const int idx = ht + 256 * i, kk = idx >> 4, vec = idx & 15;
;       if (isS && t < 8) {
;         float fk[8] = {rk[i][0].x, rk[i][0].y, rk[i][0].z, rk[i][0].w, rk[i][1].x, rk[i][1].y, rk[i][1].z, rk[i][1].w};
;         float fv[8] = {rv[i][0].x, rv[i][0].y, rv[i][0].z, rv[i][0].w, rv[i][1].x, rv[i][1].y, rv[i][1].z, rv[i][1].w};
;         *(uint4*)(Ks + kk * 136 + vec * 8) = pack8(fk);
;         *(uint4*)(Vs + kk * 136 + vec * 8) = pack8(fv);
;       } else {
;         *(uint4*)(Ks + kk * 136 + vec * 8) = kpre[i];
;         *(uint4*)(Vs + kk * 136 + vec * 8) = vpre[i];
;       }
;     }
;     __syncthreads();
;     if (t + 1 < 9) ATT_LOAD(t + 1);
;     f32x4 s[4];
; #pragma unroll
;     for (int kb = 0; kb < 4; ++kb) {
;       s[kb] = (f32x4){0.f, 0.f, 0.f, 0.f};
; #pragma unroll
;       for (int ks = 0; ks < 4; ++ks) {
;         const bf16x8 kf = *(const bf16x8*)(Ks + (kb * 16 + fr) * 136 + ks * 32 + fq * 8);
;         s[kb] = __builtin_amdgcn_mfma_f32_16x16x32_bf16(kf, qf[ks], s[kb], 0, 0, 0);
;       }
;     }
;     const int qi = wq * 16 + fr;
;     float mx = -1e30f;
; #pragma unroll
;     for (int kb = 0; kb < 4; ++kb) {
; #pragma unroll
;       for (int j = 0; j < 4; ++j) {
;         const int jb = t * 64 + kb * 16 + fq * 4 + j;
;         const bool valid = (!isS) || (jb < 528);
;         int rel = qi + 512 - jb; rel = rel < -128 ? -128 : (rel > 128 ? 128 : rel);
;         const float v = valid ? s[kb][j] * scl + Bi[rel + 128] : -1e30f;
.LBB0_517:
	s_cmp_lg_u32 s1, s15
	s_waitcnt vmcnt(7)
	ds_write_b128 v114, v[24:27]
	s_waitcnt vmcnt(6)
	ds_write_b128 v114, v[28:31] offset:18432
	s_waitcnt vmcnt(5)
	ds_write_b128 v114, v[32:35] offset:4608
	s_waitcnt vmcnt(4)
	ds_write_b128 v114, v[36:39] offset:23040
	s_waitcnt vmcnt(3)
	ds_write_b128 v114, v[40:43] offset:9216
	s_waitcnt vmcnt(2)
	ds_write_b128 v114, v[44:47] offset:27648
	s_waitcnt vmcnt(1)
	ds_write_b128 v114, v[48:51] offset:13824
	s_waitcnt vmcnt(0)
	ds_write_b128 v114, v[52:55] offset:32256
	s_waitcnt lgkmcnt(0)
	s_barrier
	s_cbranch_scc0 .LBB0_519
	v_lshl_add_u64 v[24:25], v[102:103], 0, v[100:101]
	v_add_co_u32_e32 v26, vcc, 0x17cee000, v24
	v_lshl_add_u64 v[32:33], v[108:109], 0, v[100:101]
	s_nop 0
	v_addc_co_u32_e32 v27, vcc, 0, v25, vcc
	v_add_co_u32_e32 v28, vcc, 0x17cef000, v24
	v_lshl_add_u64 v[40:41], v[106:107], 0, v[100:101]
	s_nop 0
	v_addc_co_u32_e32 v29, vcc, 0, v25, vcc
	v_add_co_u32_e32 v34, vcc, 0x17a06000, v32
	s_mov_b32 s11, 0x17a06000
	s_nop 0
	v_addc_co_u32_e32 v35, vcc, 0, v33, vcc
	v_add_co_u32_e32 v36, vcc, 0x17a07000, v32
	s_mov_b32 s10, 0x17a07000
	s_nop 0
	v_addc_co_u32_e32 v37, vcc, 0, v33, vcc
	v_add_co_u32_e32 v42, vcc, s11, v40
	v_lshl_add_u64 v[48:49], v[104:105], 0, v[100:101]
	s_nop 0
	v_addc_co_u32_e32 v43, vcc, 0, v41, vcc
	v_add_co_u32_e32 v44, vcc, s10, v40
	global_load_dwordx4 v[24:27], v[26:27], off offset:2048
	s_nop 0
	global_load_dwordx4 v[28:31], v[28:29], off offset:2048
	v_addc_co_u32_e32 v45, vcc, 0, v41, vcc
	v_add_co_u32_e32 v50, vcc, s11, v48
	global_load_dwordx4 v[32:35], v[34:35], off offset:2048
	s_nop 0
	global_load_dwordx4 v[36:39], v[36:37], off offset:2048
	v_addc_co_u32_e32 v51, vcc, 0, v49, vcc
	v_add_co_u32_e32 v52, vcc, 0x17a07000, v48
	global_load_dwordx4 v[40:43], v[42:43], off offset:2048
	s_nop 0
	global_load_dwordx4 v[44:47], v[44:45], off offset:2048
	v_addc_co_u32_e32 v53, vcc, 0, v49, vcc
	global_load_dwordx4 v[48:51], v[50:51], off offset:2048
	s_nop 0
	global_load_dwordx4 v[52:55], v[52:53], off offset:2048
.LBB0_519:
	v_add_u32_e32 v119, s15, v115
	s_add_i32 s0, s0, 1
	s_sub_i32 s15, s15, 64
	ds_read_b128 v[128:131], v2
	ds_read_b128 v[132:135], v2 offset:4608
	ds_read_b128 v[136:139], v2 offset:9216
	ds_read_b128 v[140:143], v2 offset:13824
	ds_read_b128 v[144:147], v2 offset:64
	ds_read_b128 v[148:151], v2 offset:4672
	ds_read_b128 v[152:155], v2 offset:9280
	ds_read_b128 v[156:159], v2 offset:13888
	ds_read_b128 v[160:163], v2 offset:128
	ds_read_b128 v[164:167], v2 offset:4736
	ds_read_b128 v[168:171], v2 offset:9344
	ds_read_b128 v[172:175], v2 offset:13952
	ds_read_b128 v[176:179], v2 offset:192
	ds_read_b128 v[180:183], v2 offset:4800
	ds_read_b128 v[184:187], v2 offset:9408
	ds_read_b128 v[192:195], v2 offset:14016
	v_lshl_add_u64 v[102:103], v[102:103], 0, s[52:53]
	v_lshl_add_u64 v[104:105], v[104:105], 0, s[52:53]
	v_lshl_add_u64 v[106:107], v[106:107], 0, s[52:53]
	v_lshl_add_u64 v[108:109], v[108:109], 0, s[52:53]
	s_cmp_lt_u32 s0, 6
	s_cbranch_scc1 .Lat_fastbias
	v_add_u32_e32 v225, 0x200, v119
	v_add_u32_e32 v234, 0x1ff, v119
	v_add_u32_e32 v235, 0x1fe, v119
	v_add_u32_e32 v212, 0x1fd, v119
	v_add_u32_e32 v213, 0x1f0, v119
	v_add_u32_e32 v214, 0x1ef, v119
	v_add_u32_e32 v215, 0x1ee, v119
	v_add_u32_e32 v216, 0x1ed, v119
	v_add_u32_e32 v217, 0x1e0, v119
	v_add_u32_e32 v218, 0x1df, v119
	v_add_u32_e32 v219, 0x1de, v119
	v_add_u32_e32 v220, 0x1dd, v119
	v_add_u32_e32 v221, 0x1d0, v119
	v_add_u32_e32 v222, 0x1cf, v119
	v_add_u32_e32 v223, 0x1ce, v119
	v_add_u32_e32 v224, 0x1cd, v119
	v_min_i32_e32 v225, 0x80, v225
	v_min_i32_e32 v234, 0x80, v234
	v_min_i32_e32 v235, 0x80, v235
	v_min_i32_e32 v212, 0x80, v212
	v_min_i32_e32 v213, 0x80, v213
	v_min_i32_e32 v214, 0x80, v214
	v_min_i32_e32 v215, 0x80, v215
	v_min_i32_e32 v216, 0x80, v216
	v_min_i32_e32 v217, 0x80, v217
	v_min_i32_e32 v218, 0x80, v218
	v_min_i32_e32 v219, 0x80, v219
	v_min_i32_e32 v220, 0x80, v220
	v_min_i32_e32 v221, 0x80, v221
	v_min_i32_e32 v222, 0x80, v222
	v_min_i32_e32 v223, 0x80, v223
	v_min_i32_e32 v224, 0x80, v224
	v_lshl_add_u32 v225, v225, 2, v110
	v_lshl_add_u32 v234, v234, 2, v110
	v_lshl_add_u32 v235, v235, 2, v110
	v_lshl_add_u32 v212, v212, 2, v110
	v_lshl_add_u32 v213, v213, 2, v110
	v_lshl_add_u32 v214, v214, 2, v110
	v_lshl_add_u32 v215, v215, 2, v110
	v_lshl_add_u32 v216, v216, 2, v110
	v_lshl_add_u32 v217, v217, 2, v110
	v_lshl_add_u32 v218, v218, 2, v110
	v_lshl_add_u32 v219, v219, 2, v110
	v_lshl_add_u32 v220, v220, 2, v110
	v_lshl_add_u32 v221, v221, 2, v110
	v_lshl_add_u32 v222, v222, 2, v110
	v_lshl_add_u32 v223, v223, 2, v110
	v_lshl_add_u32 v224, v224, 2, v110
	ds_read_b32 v124, v225 offset:44544
	ds_read_b32 v120, v234 offset:44544
	ds_read_b32 v125, v235 offset:44544
	ds_read_b32 v122, v212 offset:44544
	ds_read_b32 v123, v213 offset:44544
	ds_read_b32 v126, v214 offset:44544
	ds_read_b32 v97, v215 offset:44544
	ds_read_b32 v98, v216 offset:44544
	ds_read_b32 v99, v217 offset:44544
	ds_read_b32 v92, v218 offset:44544
	ds_read_b32 v121, v219 offset:44544
	ds_read_b32 v94, v220 offset:44544
	ds_read_b32 v95, v221 offset:44544
	ds_read_b32 v127, v222 offset:44544
	ds_read_b32 v93, v223 offset:44544
	ds_read_b32 v119, v224 offset:44544
	s_waitcnt lgkmcnt(15)
	s_branch .Lat_smfma

; __device__ __forceinline__ bf16x8 cat44(s16x4 a, s16x4 b) { return (bf16x8){a[0], a[1], a[2], a[3], b[0], b[1], b[2], b[3]}; }
; __device__ __forceinline__ void attn_item(KP P, int l, bool isS, int b, int c, int hp, char* smem) {
;     ...
;     f32x4 s[4];
; #pragma unroll
;     for (int kb = 0; kb < 4; ++kb) {
;       s[kb] = (f32x4){0.f, 0.f, 0.f, 0.f};
; #pragma unroll
;       for (int ks = 0; ks < 4; ++ks) {
;         const bf16x8 kf = *(const bf16x8*)(Ks + (kb * 16 + fr) * 136 + ks * 32 + fq * 8);
;         s[kb] = __builtin_amdgcn_mfma_f32_16x16x32_bf16(kf, qf[ks], s[kb], 0, 0, 0);
;       }
;     }
;     const int qi = wq * 16 + fr;
;     float mx = -1e30f;
; #pragma unroll
;     for (int kb = 0; kb < 4; ++kb) {
; #pragma unroll
;       for (int j = 0; j < 4; ++j) {
;         const int jb = t * 64 + kb * 16 + fq * 4 + j;
;         const bool valid = (!isS) || (jb < 528);
;         int rel = qi + 512 - jb; rel = rel < -128 ? -128 : (rel > 128 ? 128 : rel);
;         const float v = valid ? s[kb][j] * scl + Bi[rel + 128] : -1e30f;
;     ...
;     const int trr = fq * 4 + ((lane >> 2) & 3), trc = (lane & 3) * 4;
; #pragma unroll
;     for (int db = 0; db < 8; ++db) {
; #pragma unroll
;       for (int kr = 0; kr < 2; ++kr) {
;         const u16* p0 = Vs + (kr * 32 + trr) * 136 + db * 16 + trc;
;         const bf16x8 vf = cat44(ldtr(p0), ldtr(p0 + 16 * 136));
.Lat_smfma:
	v_mfma_f32_16x16x32_bf16 v[196:199], v[128:131], v[16:19], 0
	v_mfma_f32_16x16x32_bf16 v[200:203], v[132:135], v[16:19], 0
	v_mfma_f32_16x16x32_bf16 v[204:207], v[136:139], v[16:19], 0
	v_mfma_f32_16x16x32_bf16 v[208:211], v[140:143], v[16:19], 0
	v_mfma_f32_16x16x32_bf16 v[196:199], v[144:147], v[8:11], v[196:199]
	v_mfma_f32_16x16x32_bf16 v[200:203], v[148:151], v[8:11], v[200:203]
	v_mfma_f32_16x16x32_bf16 v[204:207], v[152:155], v[8:11], v[204:207]
	v_mfma_f32_16x16x32_bf16 v[208:211], v[156:159], v[8:11], v[208:211]
	v_mfma_f32_16x16x32_bf16 v[196:199], v[160:163], v[12:15], v[196:199]
	v_mfma_f32_16x16x32_bf16 v[200:203], v[164:167], v[12:15], v[200:203]
	v_mfma_f32_16x16x32_bf16 v[204:207], v[168:171], v[12:15], v[204:207]
	v_mfma_f32_16x16x32_bf16 v[208:211], v[172:175], v[12:15], v[208:211]
	v_mfma_f32_16x16x32_bf16 v[196:199], v[176:179], v[20:23], v[196:199]
	v_mfma_f32_16x16x32_bf16 v[200:203], v[180:183], v[20:23], v[200:203]
	v_mfma_f32_16x16x32_bf16 v[204:207], v[184:187], v[20:23], v[204:207]
	v_mfma_f32_16x16x32_bf16 v[208:211], v[192:195], v[20:23], v[208:211]
	ds_read_b64_tr_b16 v[128:129], v116 offset:18432
	ds_read_b64_tr_b16 v[130:131], v116 offset:23040
	ds_read_b64_tr_b16 v[132:133], v116 offset:27648
	ds_read_b64_tr_b16 v[134:135], v116 offset:32256
	ds_read_b64_tr_b16 v[136:137], v116 offset:18464
	ds_read_b64_tr_b16 v[138:139], v116 offset:23072
	ds_read_b64_tr_b16 v[140:141], v116 offset:27680
	ds_read_b64_tr_b16 v[142:143], v116 offset:32288
	ds_read_b64_tr_b16 v[144:145], v116 offset:18496
	ds_read_b64_tr_b16 v[146:147], v116 offset:23104
	ds_read_b64_tr_b16 v[148:149], v116 offset:27712
	ds_read_b64_tr_b16 v[150:151], v116 offset:32320
	ds_read_b64_tr_b16 v[152:153], v116 offset:18528
	ds_read_b64_tr_b16 v[154:155], v116 offset:23136
	ds_read_b64_tr_b16 v[156:157], v116 offset:27744
	ds_read_b64_tr_b16 v[158:159], v116 offset:32352
	s_cmp_lt_u32 s0, 6
	s_cbranch_scc1 .Lat_fastscore
	s_waitcnt lgkmcnt(15)
	v_fmac_f32_e32 v124, 0x3db504f3, v196
	v_fmac_f32_e32 v120, 0x3db504f3, v197
	v_fmac_f32_e32 v125, 0x3db504f3, v198
	v_fmac_f32_e32 v122, 0x3db504f3, v199
	v_fmac_f32_e32 v123, 0x3db504f3, v200
	v_fmac_f32_e32 v126, 0x3db504f3, v201
	v_fmac_f32_e32 v97, 0x3db504f3, v202
	v_fmac_f32_e32 v98, 0x3db504f3, v203
	v_fmac_f32_e32 v99, 0x3db504f3, v204
	v_fmac_f32_e32 v92, 0x3db504f3, v205
	v_fmac_f32_e32 v121, 0x3db504f3, v206
	v_fmac_f32_e32 v94, 0x3db504f3, v207
	v_fmac_f32_e32 v95, 0x3db504f3, v208
	v_fmac_f32_e32 v127, 0x3db504f3, v209
	v_fmac_f32_e32 v93, 0x3db504f3, v210
	v_fmac_f32_e32 v119, 0x3db504f3, v211
	s_branch .Lat_max

; __device__ __forceinline__ bf16x8 cat44(s16x4 a, s16x4 b) { return (bf16x8){a[0], a[1], a[2], a[3], b[0], b[1], b[2], b[3]}; }
; __device__ __forceinline__ void attn_item(KP P, int l, bool isS, int b, int c, int hp, char* smem) {
;     ...
;     mx = fmaxf(mx, sx<16>(mx));
;     mx = fmaxf(mx, bperm(mx, lane ^ 32));
;     const float mn = fmaxf(mrow, mx);
;     const float alpha = __expf(mrow - mn);
;     mrow = mn;
;     lrow *= alpha;
;     bf16x8 pf[2];
; #pragma unroll
;     for (int kr = 0; kr < 2; ++kr) {
;       float p[8];
; #pragma unroll
;       for (int i = 0; i < 8; ++i) {
;         const int kb = kr * 2 + (i >> 2), j = i & 3;
;         const int jb = t * 64 + kb * 16 + fq * 4 + j;
;         const bool valid = (!isS) || (jb < 528);
;         p[i] = valid ? __expf(s[kb][j] - mn) : 0.f;
;         lrow += p[i];
;       }
;       pf[kr] = as_bf16x8(pack8(p));
;     }
; #pragma unroll
;     for (int db = 0; db < 8; ++db) {
; #pragma unroll
;       for (int j = 0; j < 4; ++j) o[db][j] *= alpha;
;     }
;     const int trr = fq * 4 + ((lane >> 2) & 3), trc = (lane & 3) * 4;
; #pragma unroll
;     for (int db = 0; db < 8; ++db) {
; #pragma unroll
;       for (int kr = 0; kr < 2; ++kr) {
;         const u16* p0 = Vs + (kr * 32 + trr) * 136 + db * 16 + trc;
;         const bf16x8 vf = cat44(ldtr(p0), ldtr(p0 + 16 * 136));
;         o[db] = __builtin_amdgcn_mfma_f32_16x16x32_bf16(vf, pf[kr], o[db], 0, 0, 0);
;       }
;     }
;     __syncthreads();
;   }
.Lat_max:
	v_max3_f32 v88, v124, s34, v120
	v_max3_f32 v88, v88, v125, v122
	v_max3_f32 v88, v88, v123, v126
	v_max3_f32 v88, v88, v97, v98
	v_max3_f32 v88, v88, v99, v92
	v_max3_f32 v88, v88, v121, v94
	v_max3_f32 v88, v88, v95, v127
	v_max3_f32 v88, v88, v93, v119
	ds_swizzle_b32 v89, v88 offset:swizzle(SWAP,16)
	s_waitcnt lgkmcnt(0)
	v_max_f32_e32 v89, v89, v89
	v_max_f32_e32 v88, v88, v89
	ds_bpermute_b32 v89, v113, v88
	s_waitcnt lgkmcnt(0)
	ds_read_b64_tr_b16 v[160:161], v116 offset:18560
	ds_read_b64_tr_b16 v[162:163], v116 offset:23168
	ds_read_b64_tr_b16 v[164:165], v116 offset:27776
	ds_read_b64_tr_b16 v[166:167], v116 offset:32384
	ds_read_b64_tr_b16 v[168:169], v116 offset:18592
	ds_read_b64_tr_b16 v[170:171], v116 offset:23200
	ds_read_b64_tr_b16 v[172:173], v116 offset:27808
	ds_read_b64_tr_b16 v[174:175], v116 offset:32416
	ds_read_b64_tr_b16 v[176:177], v116 offset:18624
	ds_read_b64_tr_b16 v[178:179], v116 offset:23232
	ds_read_b64_tr_b16 v[180:181], v116 offset:27840
	ds_read_b64_tr_b16 v[182:183], v116 offset:32448
	ds_read_b64_tr_b16 v[184:185], v116 offset:18656
	ds_read_b64_tr_b16 v[186:187], v116 offset:23264
	ds_read_b64_tr_b16 v[192:193], v116 offset:27872
	ds_read_b64_tr_b16 v[194:195], v116 offset:32480
	v_max3_f32 v96, v118, v88, v89
	v_sub_f32_e32 v88, v118, v96
	v_mul_f32_e32 v88, 0x3fb8aa3b, v88
	v_exp_f32_e32 v118, v88
	v_sub_f32_e32 v88, v124, v96
	v_mul_f32_e32 v88, 0x3fb8aa3b, v88
	v_exp_f32_e32 v88, v88
	v_sub_f32_e32 v90, v120, v96
	v_mul_f32_e32 v90, 0x3fb8aa3b, v90
	v_sub_f32_e32 v91, v125, v96
	v_fma_f32 v89, v117, v118, v88
	v_exp_f32_e32 v90, v90
	v_mul_f32_e32 v91, 0x3fb8aa3b, v91
	v_sub_f32_e32 v117, v122, v96
	v_exp_f32_e32 v91, v91
	v_mul_f32_e32 v117, 0x3fb8aa3b, v117
	v_sub_f32_e32 v120, v123, v96
	v_exp_f32_e32 v117, v117
	v_mul_f32_e32 v120, 0x3fb8aa3b, v120
	v_sub_f32_e32 v122, v126, v96
	v_exp_f32_e32 v120, v120
	v_mul_f32_e32 v122, 0x3fb8aa3b, v122
	v_sub_f32_e32 v97, v97, v96
	v_add_f32_e32 v89, v90, v89
	v_exp_f32_e32 v122, v122
	v_mul_f32_e32 v97, 0x3fb8aa3b, v97
	v_sub_f32_e32 v98, v98, v96
	v_add_f32_e32 v89, v91, v89
	v_exp_f32_e32 v97, v97
	v_mul_f32_e32 v98, 0x3fb8aa3b, v98
	v_add_f32_e32 v89, v117, v89
	v_exp_f32_e32 v98, v98
	v_add_f32_e32 v89, v120, v89
	v_add_f32_e32 v89, v122, v89
	v_add_f32_e32 v89, v97, v89
	v_bfe_u32 v124, v122, 16, 1
	v_bfe_u32 v125, v117, 16, 1
	v_bfe_u32 v126, v90, 16, 1
	v_add_f32_e32 v123, v98, v89
	v_bfe_u32 v89, v98, 16, 1
	v_add3_u32 v126, v90, v126, s33
	v_add3_u32 v117, v117, v125, s33
	v_add3_u32 v90, v122, v124, s33
	v_bfe_u32 v122, v91, 16, 1
	v_bfe_u32 v125, v97, 16, 1
	v_add3_u32 v89, v98, v89, s33
	v_bfe_u32 v98, v88, 16, 1
	v_add3_u32 v97, v97, v125, s33
	v_add3_u32 v91, v91, v122, s33
	v_add3_u32 v88, v88, v98, s33
	v_lshrrev_b32_e32 v98, 16, v91
	v_lshrrev_b32_e32 v91, 16, v97
	v_sub_f32_e32 v97, v99, v96
	v_mul_f32_e32 v97, 0x3fb8aa3b, v97
	v_sub_f32_e32 v92, v92, v96
	v_and_or_b32 v91, v89, s30, v91
	v_and_or_b32 v89, v117, s30, v98
	v_exp_f32_e32 v99, v97
	v_mul_f32_e32 v92, 0x3fb8aa3b, v92
	v_sub_f32_e32 v98, v121, v96
	v_bfe_u32 v124, v120, 16, 1
	v_exp_f32_e32 v92, v92
	v_mul_f32_e32 v98, 0x3fb8aa3b, v98
	v_sub_f32_e32 v94, v94, v96
	v_add3_u32 v120, v120, v124, s33
	v_exp_f32_e32 v117, v98
	v_mul_f32_e32 v94, 0x3fb8aa3b, v94
	v_sub_f32_e32 v95, v95, v96
	v_sub_f32_e32 v98, v127, v96
	v_lshrrev_b32_e32 v120, 16, v120
	v_exp_f32_e32 v94, v94
	v_mul_f32_e32 v95, 0x3fb8aa3b, v95
	v_mul_f32_e32 v98, 0x3fb8aa3b, v98
	v_sub_f32_e32 v93, v93, v96
	v_and_or_b32 v90, v90, s30, v120
	v_add_f32_e32 v97, v99, v123
	v_exp_f32_e32 v95, v95
	v_exp_f32_e32 v120, v98
	v_mul_f32_e32 v93, 0x3fb8aa3b, v93
	v_sub_f32_e32 v98, v119, v96
	v_add_f32_e32 v97, v92, v97
	v_exp_f32_e32 v93, v93
	v_mul_f32_e32 v98, 0x3fb8aa3b, v98
	v_add_f32_e32 v97, v117, v97
	v_exp_f32_e32 v98, v98
	v_add_f32_e32 v97, v94, v97
	v_add_f32_e32 v97, v95, v97
	v_bfe_u32 v121, v120, 16, 1
	v_bfe_u32 v122, v94, 16, 1
	v_bfe_u32 v123, v92, 16, 1
	v_add_f32_e32 v97, v120, v97
	v_add3_u32 v92, v92, v123, s33
	v_add3_u32 v122, v94, v122, s33
	v_add3_u32 v94, v120, v121, s33
	v_bfe_u32 v121, v117, 16, 1
	v_bfe_u32 v123, v95, 16, 1
	v_bfe_u32 v124, v93, 16, 1
	v_add_f32_e32 v97, v93, v97
	v_bfe_u32 v119, v98, 16, 1
	v_bfe_u32 v120, v99, 16, 1
	v_add3_u32 v93, v93, v124, s33
	v_add3_u32 v95, v95, v123, s33
	v_add3_u32 v117, v117, v121, s33
	v_add3_u32 v119, v98, v119, s33
	v_add3_u32 v99, v99, v120, s33
	v_lshrrev_b32_e32 v117, 16, v117
	v_lshrrev_b32_e32 v120, 16, v95
	v_lshrrev_b32_e32 v93, 16, v93
	v_and_or_b32 v95, v119, s30, v93
	v_and_or_b32 v94, v94, s30, v120
	v_and_or_b32 v93, v122, s30, v117
	v_pk_mul_f32 v[66:67], v[66:67], v[118:119] op_sel_hi:[1,0]
	v_pk_mul_f32 v[64:65], v[64:65], v[118:119] op_sel_hi:[1,0]
	v_pk_mul_f32 v[58:59], v[58:59], v[118:119] op_sel_hi:[1,0]
	v_pk_mul_f32 v[56:57], v[56:57], v[118:119] op_sel_hi:[1,0]
	v_pk_mul_f32 v[62:63], v[62:63], v[118:119] op_sel_hi:[1,0]
	v_pk_mul_f32 v[60:61], v[60:61], v[118:119] op_sel_hi:[1,0]
	v_pk_mul_f32 v[74:75], v[74:75], v[118:119] op_sel_hi:[1,0]
	v_pk_mul_f32 v[72:73], v[72:73], v[118:119] op_sel_hi:[1,0]
	v_pk_mul_f32 v[78:79], v[78:79], v[118:119] op_sel_hi:[1,0]
	v_pk_mul_f32 v[76:77], v[76:77], v[118:119] op_sel_hi:[1,0]
	v_pk_mul_f32 v[70:71], v[70:71], v[118:119] op_sel_hi:[1,0]
	v_pk_mul_f32 v[68:69], v[68:69], v[118:119] op_sel_hi:[1,0]
	v_pk_mul_f32 v[82:83], v[82:83], v[118:119] op_sel_hi:[1,0]
	v_pk_mul_f32 v[80:81], v[80:81], v[118:119] op_sel_hi:[1,0]
	v_pk_mul_f32 v[86:87], v[86:87], v[118:119] op_sel_hi:[1,0]
	v_pk_mul_f32 v[84:85], v[84:85], v[118:119] op_sel_hi:[1,0]
	v_lshrrev_b32_e32 v88, 16, v88
	v_and_or_b32 v88, v126, s30, v88
	v_lshrrev_b32_e32 v99, 16, v99
	v_and_or_b32 v92, v92, s30, v99
	v_add_f32_e32 v117, v98, v97
	s_waitcnt lgkmcnt(0)
	s_barrier
	v_mfma_f32_16x16x32_bf16 v[64:67], v[128:131], v[88:91], v[64:67]
	v_mfma_f32_16x16x32_bf16 v[64:67], v[132:135], v[92:95], v[64:67]
	v_mfma_f32_16x16x32_bf16 v[56:59], v[136:139], v[88:91], v[56:59]
	v_mfma_f32_16x16x32_bf16 v[56:59], v[140:143], v[92:95], v[56:59]
	v_mfma_f32_16x16x32_bf16 v[60:63], v[144:147], v[88:91], v[60:63]
	v_mfma_f32_16x16x32_bf16 v[60:63], v[148:151], v[92:95], v[60:63]
	v_mfma_f32_16x16x32_bf16 v[72:75], v[152:155], v[88:91], v[72:75]
	v_mfma_f32_16x16x32_bf16 v[72:75], v[156:159], v[92:95], v[72:75]
	v_mfma_f32_16x16x32_bf16 v[76:79], v[160:163], v[88:91], v[76:79]
	v_mfma_f32_16x16x32_bf16 v[76:79], v[164:167], v[92:95], v[76:79]
	v_mfma_f32_16x16x32_bf16 v[68:71], v[168:171], v[88:91], v[68:71]
	v_mfma_f32_16x16x32_bf16 v[68:71], v[172:175], v[92:95], v[68:71]
	v_mfma_f32_16x16x32_bf16 v[80:83], v[176:179], v[88:91], v[80:83]
	v_mfma_f32_16x16x32_bf16 v[80:83], v[180:183], v[92:95], v[80:83]
	v_mfma_f32_16x16x32_bf16 v[84:87], v[184:187], v[88:91], v[84:87]
	v_mfma_f32_16x16x32_bf16 v[84:87], v[192:195], v[92:95], v[84:87]
	s_cmp_gt_u32 s0, 7
	s_cbranch_scc1 .LBB0_513
	v_mov_b32_e32 v118, v96
	s_branch .LBB0_517
